# mLSTM chain: output stores straight-line with the 4 normaliser LDS reads issued together and one base address per chunk
# speedup vs baseline: 1.1000x; 1.0051x over previous
; __device__ __forceinline__ bf16_t f2bf(float f) { unsigned u = __float_as_uint(f); u += 0x7FFFu + ((u >> 16) & 1u); return (bf16_t)(u >> 16); }
; __device__ __forceinline__ void mlstm_task(const Ctx& c, int p, int l, int q, int h, int slab) {
;     ...
;         for (int r = 0; r < 4; ++r) { const int t = 16 * ti + (lane >> 4) * 4 + r; num[r] = qc[r] * wint[t] + esc[t] * num[r]; }
;         if (w < 4) {
;             f32x4 sv2 = {0.f, 0.f, 0.f, 0.f};
;             sv2 = mma_tile(St + 16 * w * 72, 72, VT + 32 * 72, 72, 64, sv2, lane);
; #pragma unroll
;             for (int r = 0; r < 4; ++r) { const int t = 16 * w + (lane >> 4) * 4 + r; qc2[r] = qc2[r] * wint[t] + esc[t] * sv2[r]; }
;             if ((lane & 15) == 0) {
; #pragma unroll
;                 for (int r = 0; r < 4; ++r) { const int t = 16 * w + (lane >> 4) * 4 + r; dd[t] = fmaxf(fabsf(qc2[r]), __expf(-mts[t])); }
;             }
;         }
;         __syncthreads();
; #pragma unroll
;         for (int r = 0; r < 4; ++r) {
;             const int t = 16 * ti + (lane >> 4) * 4 + r;
;             if (t < nvalid) Z[(size_t)(rbase + t) * ZW + C_V + 256 * h + slab * 32 + 16 * vj + (lane & 15)] = f2bf(num[r] * __builtin_amdgcn_rcpf(dd[t]));
;         }
.LBB0_1635:
	v_lshlrev_b32_e32 v8, 1, v90
	s_waitcnt lgkmcnt(0)
	s_barrier
	ds_read_b32 v10, v159
	ds_read_b32 v11, v160
	ds_read_b32 v84, v161
	ds_read_b32 v85, v184
	v_mul_f32_e32 v4, v4, v112
	v_fmac_f32_e32 v4, v0, v110
	v_mul_f32_e32 v5, v5, v113
	v_fmac_f32_e32 v5, v1, v111
	v_mul_f32_e32 v6, v6, v108
	v_fmac_f32_e32 v6, v2, v106
	v_mul_f32_e32 v7, v7, v109
	v_fmac_f32_e32 v7, v3, v107
	v_add_u32_e32 v0, s96, v191
	v_mov_b64_e32 v[2:3], s[72:73]
	v_mad_i64_i32 v[2:3], s[86:87], v0, s33, v[2:3]
	s_lshl_b32 s90, s88, 1
	v_lshl_add_u64 v[2:3], v[2:3], 0, s[90:91]
	s_lshl_b32 s90, s92, 1
	v_lshl_add_u64 v[2:3], v[2:3], 0, s[90:91]
	s_lshl_b32 s90, s71, 1
	v_lshl_add_u64 v[2:3], v[2:3], 0, s[90:91]
	v_mov_b32_e32 v9, v31
	v_lshl_add_u64 v[2:3], v[2:3], 0, v[8:9]
	v_add_co_u32_e32 v2, vcc, 0x1000, v2
	s_movk_i32 s90, 0x4200
	s_nop 0
	v_addc_co_u32_e32 v3, vcc, 0, v3, vcc
	v_lshl_add_u64 v[86:87], v[2:3], 0, s[90:91]
	v_lshl_add_u64 v[200:201], v[86:87], 0, s[90:91]
	v_lshl_add_u64 v[202:203], v[200:201], 0, s[90:91]
	s_waitcnt lgkmcnt(0)
	v_rcp_f32_e32 v10, v10
	v_rcp_f32_e32 v11, v11
	v_rcp_f32_e32 v84, v84
	v_rcp_f32_e32 v85, v85
	v_mul_f32_e32 v4, v4, v10
	v_mul_f32_e32 v5, v5, v11
	v_mul_f32_e32 v6, v6, v84
	v_mul_f32_e32 v7, v7, v85
	v_cvt_pk_bf16_f32 v4, v4, v5
	v_cvt_pk_bf16_f32 v6, v6, v7
	s_and_saveexec_b64 s[68:69], s[60:61]
	global_store_short v[2:3], v4, off offset:2048
	s_or_b64 exec, exec, s[68:69]
	s_and_saveexec_b64 s[68:69], s[62:63]
	global_store_short_d16_hi v[86:87], v4, off offset:2048
	s_or_b64 exec, exec, s[68:69]
	s_and_saveexec_b64 s[68:69], s[64:65]
	global_store_short v[200:201], v6, off offset:2048
	s_or_b64 exec, exec, s[68:69]
	s_and_saveexec_b64 s[68:69], s[66:67]
	global_store_short_d16_hi v[202:203], v6, off offset:2048
